# final RMSNorm: loop-invariant gain slice loaded once before the row loop
# baseline (speedup 1.0000x reference)
; DI void phase_final(const Prm& p) {
;     ...
;   for (int row = gw; row < 3 * TB; row += nw) {
;     float* xr = p.out + (size_t)row * 1024;
;     float4 v[4];
;     float ss = 0.f;
; #pragma unroll
;     for (int i = 0; i < 4; ++i) {
;       v[i] = *(const float4*)(xr + i * 256 + lane * 4);
;       ss += v[i].x * v[i].x + v[i].y * v[i].y + v[i].z * v[i].z + v[i].w * v[i].w;
;     }
; #pragma unroll
;     for (int off = 32; off >= 1; off >>= 1) ss += __shfl_xor(ss, off);
;     const float rstd = rsqrtf(ss * (1.f / 1024.f) + 1e-6f);
; #pragma unroll
;     for (int i = 0; i < 4; ++i) {
;       const int col = i * 256 + lane * 4;
;       const float4 gg = *(const float4*)(p.final_g + col);
;       float4 o;
;       o.x = v[i].x * rstd * gg.x; o.y = v[i].y * rstd * gg.y; o.z = v[i].z * rstd * gg.z; o.w = v[i].w * rstd * gg.w;
;       *(float4*)(xr + col) = o;
;     }
;   }
.LBB0_2580:
	v_readlane_b32 s0, v253, 61
	v_ashrrev_i32_e32 v0, 6, v224
	s_nop 0
	v_add_u32_e32 v0, s0, v0
	s_mov_b32 s0, 0xc000
	v_cmp_gt_i32_e32 vcc, s0, v0
	s_and_saveexec_b64 s[0:1], vcc
	v_readlane_b32 s16, v254, 13
	v_readlane_b32 s17, v254, 14
	s_cbranch_execz .LBB0_2583
	v_xor_b32_e32 v1, 32, v231
	v_cmp_lt_i32_e32 vcc, v1, v232
	v_readlane_b32 s0, v252, 24
	v_readlane_b32 s1, v252, 25
	v_cndmask_b32_e32 v1, v231, v1, vcc
	v_lshlrev_b32_e32 v6, 2, v1
	v_xor_b32_e32 v1, 16, v231
	v_cmp_lt_i32_e32 vcc, v1, v232
	v_readlane_b32 s4, v252, 28
	v_readlane_b32 s5, v252, 29
	v_cndmask_b32_e32 v1, v231, v1, vcc
	v_lshlrev_b32_e32 v7, 2, v1
	v_xor_b32_e32 v1, 8, v231
	v_cmp_lt_i32_e32 vcc, v1, v232
	v_mov_b32_e32 v3, 0
	v_readlane_b32 s2, v252, 26
	v_cndmask_b32_e32 v1, v231, v1, vcc
	v_lshlrev_b32_e32 v8, 2, v1
	v_xor_b32_e32 v1, 4, v231
	v_cmp_lt_i32_e32 vcc, v1, v232
	v_readlane_b32 s3, v252, 27
	s_mov_b64 s[0:1], 0x800
	v_cndmask_b32_e32 v1, v231, v1, vcc
	v_lshlrev_b32_e32 v9, 2, v1
	v_xor_b32_e32 v1, 2, v231
	v_cmp_lt_i32_e32 vcc, v1, v232
	v_readlane_b32 s6, v252, 30
	v_readlane_b32 s7, v252, 31
	v_cndmask_b32_e32 v1, v231, v1, vcc
	v_lshlrev_b32_e32 v10, 2, v1
	v_xor_b32_e32 v1, 1, v231
	v_cmp_lt_i32_e32 vcc, v1, v232
	v_readlane_b32 s8, v252, 32
	v_readlane_b32 s9, v252, 33
	v_cndmask_b32_e32 v1, v231, v1, vcc
	v_lshlrev_b32_e32 v11, 2, v1
	v_lshlrev_b32_e32 v1, 4, v224
	v_and_b32_e32 v2, 0x3f0, v1
	v_ashrrev_i32_e32 v1, 31, v0
	v_lshlrev_b64 v[4:5], 12, v[0:1]
	v_and_b32_e32 v1, 63, v224
	v_lshl_or_b32 v4, v1, 4, v4
	v_lshl_add_u64 v[4:5], s[4:5], 0, v[4:5]
	v_lshl_add_u64 v[2:3], s[2:3], 0, v[2:3]
	v_lshl_add_u64 v[4:5], v[4:5], 0, s[0:1]
	s_mov_b64 s[0:1], 0
	v_mov_b32_e32 v1, 0x358637bd
	s_mov_b32 s2, 0x800000
	s_mov_b32 s3, 0xbfff
	v_readlane_b32 s10, v252, 34
	v_readlane_b32 s11, v252, 35
	v_readlane_b32 s12, v252, 36
	v_readlane_b32 s13, v252, 37
	v_readlane_b32 s14, v252, 38
	v_readlane_b32 s15, v252, 39
	global_load_dwordx4 v[48:51], v[2:3], off
	global_load_dwordx4 v[52:55], v[2:3], off offset:1024
	global_load_dwordx4 v[56:59], v[2:3], off offset:2048
	global_load_dwordx4 v[60:63], v[2:3], off offset:3072
	s_waitcnt vmcnt(0)
.LBB0_2582:
	global_load_dwordx4 v[12:15], v[4:5], off offset:-2048
	global_load_dwordx4 v[16:19], v[4:5], off offset:-1024
	global_load_dwordx4 v[20:23], v[4:5], off
	global_load_dwordx4 v[24:27], v[4:5], off offset:1024
	v_add_u32_e32 v0, s84, v0
	s_waitcnt vmcnt(3)
	v_mov_b32_e32 v34, v13
	s_waitcnt vmcnt(2)
	v_mov_b32_e32 v35, v17
	v_mov_b32_e32 v32, v12
	v_mov_b32_e32 v33, v16
	s_waitcnt vmcnt(1)
	v_mov_b32_e32 v42, v21
	s_waitcnt vmcnt(0)
	v_mov_b32_e32 v43, v25
	v_pk_mul_f32 v[34:35], v[34:35], v[34:35]
	v_mov_b32_e32 v36, v14
	v_mov_b32_e32 v37, v18
	v_mov_b32_e32 v40, v20
	v_mov_b32_e32 v41, v24
	v_pk_mul_f32 v[42:43], v[42:43], v[42:43]
	v_pk_fma_f32 v[32:33], v[32:33], v[32:33], v[34:35]
	v_mov_b32_e32 v38, v15
	v_mov_b32_e32 v39, v19
	v_mov_b32_e32 v44, v22
	v_mov_b32_e32 v45, v26
	v_pk_fma_f32 v[34:35], v[40:41], v[40:41], v[42:43]
	v_pk_fma_f32 v[32:33], v[36:37], v[36:37], v[32:33]
	v_mov_b32_e32 v46, v23
	v_mov_b32_e32 v47, v27
	v_pk_fma_f32 v[34:35], v[44:45], v[44:45], v[34:35]
	v_pk_fma_f32 v[32:33], v[38:39], v[38:39], v[32:33]
	v_pk_fma_f32 v[34:35], v[46:47], v[46:47], v[34:35]
	v_add_f32_e32 v32, v32, v33
	v_add_f32_e32 v32, v32, v34
	v_add_f32_e32 v32, v32, v35
	ds_bpermute_b32 v33, v6, v32
	s_waitcnt lgkmcnt(0)
	v_add_f32_e32 v32, v32, v33
	ds_bpermute_b32 v33, v7, v32
	s_waitcnt lgkmcnt(0)
	v_add_f32_e32 v32, v32, v33
	ds_bpermute_b32 v33, v8, v32
	s_waitcnt lgkmcnt(0)
	v_add_f32_e32 v32, v32, v33
	ds_bpermute_b32 v33, v9, v32
	s_waitcnt lgkmcnt(0)
	v_add_f32_e32 v32, v32, v33
	ds_bpermute_b32 v33, v10, v32
	s_waitcnt lgkmcnt(0)
	v_add_f32_e32 v32, v32, v33
	ds_bpermute_b32 v33, v11, v32
	s_waitcnt lgkmcnt(0)
	v_add_f32_e32 v32, v32, v33
	v_fmamk_f32 v32, v32, 0x3a800000, v1
	v_mul_f32_e32 v33, 0x4b800000, v32
	v_cmp_gt_f32_e32 vcc, s2, v32
	s_nop 1
	v_cndmask_b32_e32 v32, v32, v33, vcc
	v_rsq_f32_e32 v32, v32
	s_nop 0
	v_mul_f32_e32 v33, 0x45800000, v32
	v_cndmask_b32_e32 v32, v32, v33, vcc
	v_pk_mul_f32 v[12:13], v[12:13], v[32:33] op_sel_hi:[1,0]
	v_pk_mul_f32 v[14:15], v[14:15], v[32:33] op_sel_hi:[1,0]
	v_pk_mul_f32 v[12:13], v[48:49], v[12:13]
	v_pk_mul_f32 v[14:15], v[50:51], v[14:15]
	global_store_dwordx4 v[4:5], v[12:15], off offset:-2048
	v_pk_mul_f32 v[16:17], v[16:17], v[32:33] op_sel_hi:[1,0]
	v_pk_mul_f32 v[18:19], v[18:19], v[32:33] op_sel_hi:[1,0]
	v_cmp_lt_i32_e32 vcc, s3, v0
	s_or_b64 s[0:1], vcc, s[0:1]
	v_pk_mul_f32 v[12:13], v[52:53], v[16:17]
	v_pk_mul_f32 v[14:15], v[54:55], v[18:19]
	global_store_dwordx4 v[4:5], v[12:15], off offset:-1024
	v_pk_mul_f32 v[16:17], v[20:21], v[32:33] op_sel_hi:[1,0]
	v_pk_mul_f32 v[18:19], v[22:23], v[32:33] op_sel_hi:[1,0]
	v_pk_mul_f32 v[12:13], v[16:17], v[56:57]
	v_pk_mul_f32 v[14:15], v[18:19], v[58:59]
	global_store_dwordx4 v[4:5], v[12:15], off
	v_pk_mul_f32 v[16:17], v[24:25], v[32:33] op_sel_hi:[1,0]
	v_pk_mul_f32 v[18:19], v[26:27], v[32:33] op_sel_hi:[1,0]
	v_pk_mul_f32 v[12:13], v[16:17], v[60:61]
	v_pk_mul_f32 v[14:15], v[18:19], v[62:63]
	global_store_dwordx4 v[4:5], v[12:15], off offset:1024
	v_lshl_add_u64 v[4:5], v[4:5], 0, s[16:17]
	s_andn2_b64 exec, exec, s[0:1]
	s_cbranch_execnz .LBB0_2582
